# P6: half of the epilogue residual (XB) loads issued from inside the K-loop into free registers (shorter bandwidth-bound tail)
# speedup vs baseline: 1.0061x; 1.0061x over previous
.LBB0_687:
	ds_read_b128 v[128:131], v195
	ds_read_b128 v[132:135], v195 offset:1024
	ds_read_b128 v[136:139], v195 offset:2048
	ds_read_b128 v[140:143], v195 offset:3072
	ds_read_b128 v[144:147], v196
	ds_read_b128 v[148:151], v196 offset:1024
	ds_read_b128 v[152:155], v196 offset:2048
	ds_read_b128 v[156:159], v196 offset:3072
	s_add_u32 s20, s18, 0x100
	s_addc_u32 s21, s19, 0
	s_cmp_eq_u32 s47, 40
	s_cselect_b32 s25, s5, s21
	s_cselect_b32 s24, s4, s20
	s_cselect_b32 s23, s15, s46
	s_cselect_b32 s22, s14, s45
	v_lshl_add_u64 v[214:215], s[18:19], 0, v[172:173]
	s_add_i32 m0, s29, 0xc000
	ds_read_b128 v[160:163], v197
	ds_read_b128 v[180:183], v197 offset:1024
	ds_read_b128 v[184:187], v197 offset:2048
	ds_read_b128 v[188:191], v197 offset:3072
	ds_read_b128 v[198:201], v197 offset:4096
	ds_read_b128 v[202:205], v197 offset:5120
	ds_read_b128 v[206:209], v197 offset:6144
	ds_read_b128 v[210:213], v197 offset:7168
	global_load_lds_dwordx4 v[214:215], off
	v_lshl_add_u64 v[214:215], s[18:19], 0, v[174:175]
	s_add_i32 m0, s29, 0xe000
	s_nop 0
	global_load_lds_dwordx4 v[214:215], off
	s_waitcnt vmcnt(8)
	s_cmp_lg_u32 s47, 8
	s_cbranch_scc1 .Lp6_nopf
	v_lshl_add_u32 v252, s43, 8, v192
	v_lshl_or_b32 v254, s44, 8, v194
	v_ashrrev_i32_e32 v255, 31, v254
	v_ashrrev_i32_e32 v253, 31, v252
	v_lshl_add_u64 v[254:255], v[254:255], 1, s[8:9]
	v_lshlrev_b64 v[250:251], 11, v[252:253]
	v_lshl_add_u64 v[250:251], v[254:255], 0, v[250:251]
	global_load_dwordx4 v[224:227], v[250:251], off
	global_load_dwordx4 v[228:231], v[250:251], off offset:256
	v_or_b32_e32 v250, 16, v252
	v_mov_b32_e32 v251, v253
	v_lshlrev_b64 v[250:251], 11, v[250:251]
	v_lshl_add_u64 v[250:251], v[254:255], 0, v[250:251]
	global_load_dwordx4 v[232:235], v[250:251], off
	global_load_dwordx4 v[236:239], v[250:251], off offset:256
	v_or_b32_e32 v250, 32, v252
	v_mov_b32_e32 v251, v253
	v_lshlrev_b64 v[250:251], 11, v[250:251]
	v_lshl_add_u64 v[250:251], v[254:255], 0, v[250:251]
	global_load_dwordx4 v[240:243], v[250:251], off
	global_load_dwordx4 v[244:247], v[250:251], off offset:256
	v_or_b32_e32 v250, 48, v252
	v_mov_b32_e32 v251, v253
	v_lshlrev_b64 v[250:251], 11, v[250:251]
	v_lshl_add_u64 v[250:251], v[254:255], 0, v[250:251]
	global_load_dwordx4 v[252:255], v[250:251], off offset:256
	global_load_dwordx4 v[248:251], v[250:251], off
.Lp6_nopf:
	s_waitcnt lgkmcnt(0)
	s_barrier
	s_setprio 1
	s_waitcnt lgkmcnt(0)
	v_mfma_f32_16x16x32_bf16 v[124:127], v[128:131], v[160:163], v[124:127]
	v_mfma_f32_16x16x32_bf16 v[120:123], v[136:139], v[160:163], v[120:123]
	v_mfma_f32_16x16x32_bf16 v[112:115], v[128:131], v[184:187], v[112:115]
	v_mfma_f32_16x16x32_bf16 v[104:107], v[136:139], v[184:187], v[104:107]
	v_mfma_f32_16x16x32_bf16 v[96:99], v[128:131], v[198:201], v[96:99]
	v_mfma_f32_16x16x32_bf16 v[88:91], v[136:139], v[198:201], v[88:91]
	v_mfma_f32_16x16x32_bf16 v[80:83], v[128:131], v[206:209], v[80:83]
	v_mfma_f32_16x16x32_bf16 v[72:75], v[136:139], v[206:209], v[72:75]
	v_mfma_f32_16x16x32_bf16 v[124:127], v[132:135], v[180:183], v[124:127]
	v_mfma_f32_16x16x32_bf16 v[120:123], v[140:143], v[180:183], v[120:123]
	v_mfma_f32_16x16x32_bf16 v[112:115], v[132:135], v[188:191], v[112:115]
	v_mfma_f32_16x16x32_bf16 v[104:107], v[140:143], v[188:191], v[104:107]
	v_mfma_f32_16x16x32_bf16 v[96:99], v[132:135], v[202:205], v[96:99]
	v_mfma_f32_16x16x32_bf16 v[88:91], v[140:143], v[202:205], v[88:91]
	v_mfma_f32_16x16x32_bf16 v[80:83], v[132:135], v[210:213], v[80:83]
	v_mfma_f32_16x16x32_bf16 v[72:75], v[140:143], v[210:213], v[72:75]
	s_setprio 0
	s_setprio 1
	v_mfma_f32_16x16x32_bf16 v[116:119], v[144:147], v[160:163], v[116:119]
	v_mfma_f32_16x16x32_bf16 v[108:111], v[152:155], v[160:163], v[108:111]
	v_mfma_f32_16x16x32_bf16 v[100:103], v[144:147], v[184:187], v[100:103]
	v_mfma_f32_16x16x32_bf16 v[92:95], v[152:155], v[184:187], v[92:95]
	v_mfma_f32_16x16x32_bf16 v[84:87], v[144:147], v[198:201], v[84:87]
	v_mfma_f32_16x16x32_bf16 v[76:79], v[152:155], v[198:201], v[76:79]
	v_mfma_f32_16x16x32_bf16 v[68:71], v[144:147], v[206:209], v[68:71]
	v_mfma_f32_16x16x32_bf16 v[64:67], v[152:155], v[206:209], v[64:67]
	v_mfma_f32_16x16x32_bf16 v[116:119], v[148:151], v[180:183], v[116:119]
	v_mfma_f32_16x16x32_bf16 v[108:111], v[156:159], v[180:183], v[108:111]
	v_mfma_f32_16x16x32_bf16 v[100:103], v[148:151], v[188:191], v[100:103]
	v_mfma_f32_16x16x32_bf16 v[92:95], v[156:159], v[188:191], v[92:95]
	v_mfma_f32_16x16x32_bf16 v[84:87], v[148:151], v[202:205], v[84:87]
	v_mfma_f32_16x16x32_bf16 v[76:79], v[156:159], v[202:205], v[76:79]
	v_mfma_f32_16x16x32_bf16 v[68:71], v[148:151], v[210:213], v[68:71]
	v_mfma_f32_16x16x32_bf16 v[64:67], v[156:159], v[210:213], v[64:67]
	s_setprio 0
	s_barrier
	s_add_i32 s18, s39, s28
	v_lshl_add_u64 v[214:215], s[22:23], 0, v[166:167]
	s_mov_b32 m0, s18
	ds_read_b128 v[160:163], v197 offset:16384
	ds_read_b128 v[180:183], v197 offset:17408
	ds_read_b128 v[184:187], v197 offset:18432
	ds_read_b128 v[188:191], v197 offset:19456
	ds_read_b128 v[198:201], v197 offset:20480
	ds_read_b128 v[202:205], v197 offset:21504
	ds_read_b128 v[206:209], v197 offset:22528
	ds_read_b128 v[210:213], v197 offset:23552
	global_load_lds_dwordx4 v[214:215], off
	s_add_i32 m0, s18, 0x2000
	s_add_u32 s18, s22, 0xb0000
	v_lshl_add_u64 v[216:217], s[22:23], 0, v[170:171]
	s_addc_u32 s19, s23, 0
	s_add_i32 s48, s40, s28
	global_load_lds_dwordx4 v[216:217], off
	v_lshl_add_u64 v[218:219], s[18:19], 0, v[166:167]
	s_mov_b32 m0, s48
	v_lshl_add_u64 v[220:221], s[24:25], 0, v[168:169]
	global_load_lds_dwordx4 v[218:219], off
	v_lshl_add_u64 v[218:219], s[18:19], 0, v[170:171]
	s_add_i32 m0, s48, 0x2000
	s_nop 0
	global_load_lds_dwordx4 v[218:219], off
	v_lshl_add_u64 v[218:219], s[24:25], 0, v[164:165]
	s_mov_b32 m0, s29
	s_nop 0
	global_load_lds_dwordx4 v[218:219], off
	s_mov_b32 m0, s33
	s_nop 0
	global_load_lds_dwordx4 v[220:221], off
	s_waitcnt vmcnt(8)
	s_waitcnt lgkmcnt(0)
	s_barrier
	s_setprio 1
	s_waitcnt lgkmcnt(0)
	v_mfma_f32_16x16x32_bf16 v[60:63], v[128:131], v[160:163], v[60:63]
	v_mfma_f32_16x16x32_bf16 v[56:59], v[136:139], v[160:163], v[56:59]
	v_mfma_f32_16x16x32_bf16 v[48:51], v[128:131], v[184:187], v[48:51]
	v_mfma_f32_16x16x32_bf16 v[40:43], v[136:139], v[184:187], v[40:43]
	v_mfma_f32_16x16x32_bf16 v[32:35], v[128:131], v[198:201], v[32:35]
	v_mfma_f32_16x16x32_bf16 v[24:27], v[136:139], v[198:201], v[24:27]
	v_mfma_f32_16x16x32_bf16 v[16:19], v[128:131], v[206:209], v[16:19]
	v_mfma_f32_16x16x32_bf16 v[8:11], v[136:139], v[206:209], v[8:11]
	v_mfma_f32_16x16x32_bf16 v[60:63], v[132:135], v[180:183], v[60:63]
	v_mfma_f32_16x16x32_bf16 v[56:59], v[140:143], v[180:183], v[56:59]
	v_mfma_f32_16x16x32_bf16 v[48:51], v[132:135], v[188:191], v[48:51]
	v_mfma_f32_16x16x32_bf16 v[40:43], v[140:143], v[188:191], v[40:43]
	v_mfma_f32_16x16x32_bf16 v[32:35], v[132:135], v[202:205], v[32:35]
	v_mfma_f32_16x16x32_bf16 v[24:27], v[140:143], v[202:205], v[24:27]
	v_mfma_f32_16x16x32_bf16 v[16:19], v[132:135], v[210:213], v[16:19]
	v_mfma_f32_16x16x32_bf16 v[8:11], v[140:143], v[210:213], v[8:11]
	s_setprio 0
	s_setprio 1
	v_mfma_f32_16x16x32_bf16 v[52:55], v[144:147], v[160:163], v[52:55]
	v_mfma_f32_16x16x32_bf16 v[44:47], v[152:155], v[160:163], v[44:47]
	v_mfma_f32_16x16x32_bf16 v[36:39], v[144:147], v[184:187], v[36:39]
	v_mfma_f32_16x16x32_bf16 v[28:31], v[152:155], v[184:187], v[28:31]
	v_mfma_f32_16x16x32_bf16 v[20:23], v[144:147], v[198:201], v[20:23]
	v_mfma_f32_16x16x32_bf16 v[12:15], v[152:155], v[198:201], v[12:15]
	v_mfma_f32_16x16x32_bf16 v[4:7], v[144:147], v[206:209], v[4:7]
	v_mfma_f32_16x16x32_bf16 v[0:3], v[152:155], v[206:209], v[0:3]
	v_mfma_f32_16x16x32_bf16 v[52:55], v[148:151], v[180:183], v[52:55]
	v_mfma_f32_16x16x32_bf16 v[44:47], v[156:159], v[180:183], v[44:47]
	v_mfma_f32_16x16x32_bf16 v[36:39], v[148:151], v[188:191], v[36:39]
	v_mfma_f32_16x16x32_bf16 v[28:31], v[156:159], v[188:191], v[28:31]
	v_mfma_f32_16x16x32_bf16 v[20:23], v[148:151], v[202:205], v[20:23]
	v_mfma_f32_16x16x32_bf16 v[12:15], v[156:159], v[202:205], v[12:15]
	v_mfma_f32_16x16x32_bf16 v[4:7], v[148:151], v[210:213], v[4:7]
	v_mfma_f32_16x16x32_bf16 v[0:3], v[156:159], v[210:213], v[0:3]
	s_setprio 0
	s_barrier
	s_add_i32 s48, 0, 0x18000
	s_add_i32 s49, 0, 0x1c000
	v_add_u32_e32 v140, s48, v193
	v_add_u32_e32 v156, s49, v193
	ds_read_b128 v[128:131], v140
	ds_read_b128 v[132:135], v140 offset:1024
	ds_read_b128 v[136:139], v140 offset:2048
	ds_read_b128 v[140:143], v140 offset:3072
	ds_read_b128 v[144:147], v156
	ds_read_b128 v[148:151], v156 offset:1024
	ds_read_b128 v[152:155], v156 offset:2048
	ds_read_b128 v[156:159], v156 offset:3072
	s_add_u32 s18, s24, 0xb0000
	s_addc_u32 s19, s25, 0
	s_mov_b32 m0, s34
	v_lshl_add_u64 v[222:223], s[18:19], 0, v[164:165]
	ds_read_b128 v[160:163], v197 offset:32768
	ds_read_b128 v[180:183], v197 offset:33792
	ds_read_b128 v[184:187], v197 offset:34816
	ds_read_b128 v[188:191], v197 offset:35840
	ds_read_b128 v[198:201], v197 offset:36864
	ds_read_b128 v[202:205], v197 offset:37888
	ds_read_b128 v[206:209], v197 offset:38912
	ds_read_b128 v[210:213], v197 offset:39936
	global_load_lds_dwordx4 v[222:223], off
	v_lshl_add_u64 v[222:223], s[18:19], 0, v[168:169]
	s_mov_b32 m0, s35
	s_nop 0
	global_load_lds_dwordx4 v[222:223], off
	s_waitcnt vmcnt(8)
	s_waitcnt lgkmcnt(0)
	s_barrier
	s_setprio 1
	s_waitcnt lgkmcnt(0)
	v_mfma_f32_16x16x32_bf16 v[124:127], v[128:131], v[160:163], v[124:127]
	v_mfma_f32_16x16x32_bf16 v[120:123], v[136:139], v[160:163], v[120:123]
	v_mfma_f32_16x16x32_bf16 v[112:115], v[128:131], v[184:187], v[112:115]
	v_mfma_f32_16x16x32_bf16 v[104:107], v[136:139], v[184:187], v[104:107]
	v_mfma_f32_16x16x32_bf16 v[96:99], v[128:131], v[198:201], v[96:99]
	v_mfma_f32_16x16x32_bf16 v[88:91], v[136:139], v[198:201], v[88:91]
	v_mfma_f32_16x16x32_bf16 v[80:83], v[128:131], v[206:209], v[80:83]
	v_mfma_f32_16x16x32_bf16 v[72:75], v[136:139], v[206:209], v[72:75]
	v_mfma_f32_16x16x32_bf16 v[124:127], v[132:135], v[180:183], v[124:127]
	v_mfma_f32_16x16x32_bf16 v[120:123], v[140:143], v[180:183], v[120:123]
	v_mfma_f32_16x16x32_bf16 v[112:115], v[132:135], v[188:191], v[112:115]
	v_mfma_f32_16x16x32_bf16 v[104:107], v[140:143], v[188:191], v[104:107]
	v_mfma_f32_16x16x32_bf16 v[96:99], v[132:135], v[202:205], v[96:99]
	v_mfma_f32_16x16x32_bf16 v[88:91], v[140:143], v[202:205], v[88:91]
	v_mfma_f32_16x16x32_bf16 v[80:83], v[132:135], v[210:213], v[80:83]
	v_mfma_f32_16x16x32_bf16 v[72:75], v[140:143], v[210:213], v[72:75]
	s_setprio 0
	s_setprio 1
	v_mfma_f32_16x16x32_bf16 v[116:119], v[144:147], v[160:163], v[116:119]
	v_mfma_f32_16x16x32_bf16 v[108:111], v[152:155], v[160:163], v[108:111]
	v_mfma_f32_16x16x32_bf16 v[100:103], v[144:147], v[184:187], v[100:103]
	v_mfma_f32_16x16x32_bf16 v[92:95], v[152:155], v[184:187], v[92:95]
	v_mfma_f32_16x16x32_bf16 v[84:87], v[144:147], v[198:201], v[84:87]
	v_mfma_f32_16x16x32_bf16 v[76:79], v[152:155], v[198:201], v[76:79]
	v_mfma_f32_16x16x32_bf16 v[68:71], v[144:147], v[206:209], v[68:71]
	v_mfma_f32_16x16x32_bf16 v[64:67], v[152:155], v[206:209], v[64:67]
	v_mfma_f32_16x16x32_bf16 v[116:119], v[148:151], v[180:183], v[116:119]
	v_mfma_f32_16x16x32_bf16 v[108:111], v[156:159], v[180:183], v[108:111]
	v_mfma_f32_16x16x32_bf16 v[100:103], v[148:151], v[188:191], v[100:103]
	v_mfma_f32_16x16x32_bf16 v[92:95], v[156:159], v[188:191], v[92:95]
	v_mfma_f32_16x16x32_bf16 v[84:87], v[148:151], v[202:205], v[84:87]
	v_mfma_f32_16x16x32_bf16 v[76:79], v[156:159], v[202:205], v[76:79]
	v_mfma_f32_16x16x32_bf16 v[68:71], v[148:151], v[210:213], v[68:71]
	v_mfma_f32_16x16x32_bf16 v[64:67], v[156:159], v[210:213], v[64:67]
	s_setprio 0
	s_barrier
	s_add_i32 s18, s48, s28
	v_lshl_add_u64 v[214:215], v[214:215], 0, s[10:11]
	s_mov_b32 m0, s18
	ds_read_b128 v[160:163], v197 offset:49152
	ds_read_b128 v[180:183], v197 offset:50176
	ds_read_b128 v[184:187], v197 offset:51200
	ds_read_b128 v[188:191], v197 offset:52224
	ds_read_b128 v[198:201], v197 offset:53248
	ds_read_b128 v[202:205], v197 offset:54272
	ds_read_b128 v[206:209], v197 offset:55296
	ds_read_b128 v[210:213], v197 offset:56320
	global_load_lds_dwordx4 v[214:215], off
	s_add_i32 m0, s18, 0x2000
	s_add_u32 s18, s22, 0xb0080
	v_lshl_add_u64 v[214:215], v[216:217], 0, s[10:11]
	s_addc_u32 s19, s23, 0
	s_add_i32 s22, s49, s28
	global_load_lds_dwordx4 v[214:215], off
	v_lshl_add_u64 v[214:215], s[18:19], 0, v[166:167]
	s_mov_b32 m0, s22
	s_nop 0
	global_load_lds_dwordx4 v[214:215], off
	v_lshl_add_u64 v[214:215], s[18:19], 0, v[170:171]
	s_add_i32 m0, s22, 0x2000
	s_nop 0
	global_load_lds_dwordx4 v[214:215], off
	v_lshl_add_u64 v[214:215], v[218:219], 0, s[10:11]
	s_mov_b32 m0, s37
	s_nop 0
	global_load_lds_dwordx4 v[214:215], off
	v_lshl_add_u64 v[214:215], v[220:221], 0, s[10:11]
	s_mov_b32 m0, s38
	s_nop 0
	global_load_lds_dwordx4 v[214:215], off
	s_waitcnt vmcnt(8)
	s_waitcnt lgkmcnt(0)
	s_barrier
	s_setprio 1
	s_waitcnt lgkmcnt(0)
	v_mfma_f32_16x16x32_bf16 v[60:63], v[128:131], v[160:163], v[60:63]
	v_mfma_f32_16x16x32_bf16 v[56:59], v[136:139], v[160:163], v[56:59]
	v_mfma_f32_16x16x32_bf16 v[48:51], v[128:131], v[184:187], v[48:51]
	v_mfma_f32_16x16x32_bf16 v[40:43], v[136:139], v[184:187], v[40:43]
	v_mfma_f32_16x16x32_bf16 v[32:35], v[128:131], v[198:201], v[32:35]
	v_mfma_f32_16x16x32_bf16 v[24:27], v[136:139], v[198:201], v[24:27]
	v_mfma_f32_16x16x32_bf16 v[16:19], v[128:131], v[206:209], v[16:19]
	v_mfma_f32_16x16x32_bf16 v[8:11], v[136:139], v[206:209], v[8:11]
	v_mfma_f32_16x16x32_bf16 v[60:63], v[132:135], v[180:183], v[60:63]
	v_mfma_f32_16x16x32_bf16 v[56:59], v[140:143], v[180:183], v[56:59]
	v_mfma_f32_16x16x32_bf16 v[48:51], v[132:135], v[188:191], v[48:51]
	v_mfma_f32_16x16x32_bf16 v[40:43], v[140:143], v[188:191], v[40:43]
	v_mfma_f32_16x16x32_bf16 v[32:35], v[132:135], v[202:205], v[32:35]
	v_mfma_f32_16x16x32_bf16 v[24:27], v[140:143], v[202:205], v[24:27]
	v_mfma_f32_16x16x32_bf16 v[16:19], v[132:135], v[210:213], v[16:19]
	v_mfma_f32_16x16x32_bf16 v[8:11], v[140:143], v[210:213], v[8:11]
	s_setprio 0
	s_setprio 1
	v_mfma_f32_16x16x32_bf16 v[52:55], v[144:147], v[160:163], v[52:55]
	v_mfma_f32_16x16x32_bf16 v[44:47], v[152:155], v[160:163], v[44:47]
	v_mfma_f32_16x16x32_bf16 v[36:39], v[144:147], v[184:187], v[36:39]
	v_mfma_f32_16x16x32_bf16 v[28:31], v[152:155], v[184:187], v[28:31]
	v_mfma_f32_16x16x32_bf16 v[20:23], v[144:147], v[198:201], v[20:23]
	v_mfma_f32_16x16x32_bf16 v[12:15], v[152:155], v[198:201], v[12:15]
	v_mfma_f32_16x16x32_bf16 v[4:7], v[144:147], v[206:209], v[4:7]
	v_mfma_f32_16x16x32_bf16 v[0:3], v[152:155], v[206:209], v[0:3]
	v_mfma_f32_16x16x32_bf16 v[52:55], v[148:151], v[180:183], v[52:55]
	v_mfma_f32_16x16x32_bf16 v[44:47], v[156:159], v[180:183], v[44:47]
	v_mfma_f32_16x16x32_bf16 v[36:39], v[148:151], v[188:191], v[36:39]
	v_mfma_f32_16x16x32_bf16 v[28:31], v[156:159], v[188:191], v[28:31]
	v_mfma_f32_16x16x32_bf16 v[20:23], v[148:151], v[202:205], v[20:23]
	v_mfma_f32_16x16x32_bf16 v[12:15], v[156:159], v[202:205], v[12:15]
	v_mfma_f32_16x16x32_bf16 v[4:7], v[148:151], v[210:213], v[4:7]
	v_mfma_f32_16x16x32_bf16 v[0:3], v[156:159], v[210:213], v[0:3]
	s_setprio 0
	s_barrier
	s_add_i32 s47, s47, 2
	s_add_u32 s45, s45, 0x100
	s_addc_u32 s46, s46, 0
	s_cmp_gt_u32 s47, 41
	s_mov_b64 s[18:19], s[20:21]
	s_cbranch_scc0 .LBB0_687
	s_and_b64 vcc, exec, s[12:13]
	s_cbranch_vccz .LBB0_690
	s_barrier
.LBB0_690:
	v_mov_b64_e32 v[198:199], v[224:225]
	v_mov_b64_e32 v[200:201], v[226:227]
	v_mov_b64_e32 v[202:203], v[228:229]
	v_mov_b64_e32 v[204:205], v[230:231]
	v_mov_b64_e32 v[206:207], v[232:233]
	v_mov_b64_e32 v[208:209], v[234:235]
	v_mov_b64_e32 v[210:211], v[236:237]
	v_mov_b64_e32 v[212:213], v[238:239]
	v_mov_b64_e32 v[214:215], v[240:241]
	v_mov_b64_e32 v[216:217], v[242:243]
	v_mov_b64_e32 v[218:219], v[244:245]
	v_mov_b64_e32 v[220:221], v[246:247]
	v_mov_b64_e32 v[160:161], v[252:253]
	v_mov_b64_e32 v[162:163], v[254:255]
	v_mov_b64_e32 v[222:223], v[248:249]
	v_mov_b64_e32 v[224:225], v[250:251]
	v_lshl_add_u32 v128, s43, 8, v192
	v_lshl_or_b32 v130, s44, 8, v194
	v_ashrrev_i32_e32 v131, 31, v130
	v_ashrrev_i32_e32 v129, 31, v128
	v_lshl_add_u64 v[132:133], v[130:131], 1, s[8:9]
	v_lshlrev_b64 v[134:135], 11, v[128:129]
	v_or_b32_e32 v226, 16, v128
	v_lshl_add_u64 v[134:135], v[132:133], 0, v[134:135]
	v_ashrrev_i32_e32 v227, 31, v226
	v_lshlrev_b64 v[134:135], 11, v[226:227]
	v_lshl_add_u64 v[134:135], v[132:133], 0, v[134:135]
	v_or_b32_e32 v228, 32, v128
	v_ashrrev_i32_e32 v229, 31, v228
	v_lshlrev_b64 v[182:183], 2, v[130:131]
	v_lshlrev_b64 v[130:131], 11, v[228:229]
	v_lshl_add_u64 v[130:131], v[132:133], 0, v[130:131]
	v_or_b32_e32 v190, 48, v128
	v_add_u32_e32 v188, 0x80, v128
	v_add_u32_e32 v186, 0x90, v128
	v_add_u32_e32 v184, 0xa0, v128
	v_add_u32_e32 v180, 0xb0, v128
	v_ashrrev_i32_e32 v191, 31, v190
	v_ashrrev_i32_e32 v189, 31, v188
	v_ashrrev_i32_e32 v187, 31, v186
	v_ashrrev_i32_e32 v185, 31, v184
	v_ashrrev_i32_e32 v181, 31, v180
	v_lshlrev_b64 v[128:129], 12, v[128:129]
	v_lshlrev_b64 v[134:135], 11, v[190:191]
	v_lshlrev_b64 v[136:137], 11, v[188:189]
	v_lshlrev_b64 v[138:139], 11, v[186:187]
	v_lshlrev_b64 v[140:141], 11, v[184:185]
	v_lshlrev_b64 v[142:143], 11, v[180:181]
	v_lshl_add_u64 v[128:129], s[68:69], 0, v[128:129]
	v_lshl_add_u64 v[134:135], v[132:133], 0, v[134:135]
	v_lshl_add_u64 v[136:137], v[132:133], 0, v[136:137]
	v_lshl_add_u64 v[138:139], v[132:133], 0, v[138:139]
	v_lshl_add_u64 v[230:231], v[132:133], 0, v[140:141]
	v_lshl_add_u64 v[232:233], v[132:133], 0, v[142:143]
	v_lshl_add_u64 v[234:235], v[128:129], 0, v[182:183]
	global_load_dwordx4 v[156:159], v[136:137], off
	global_load_dwordx4 v[152:155], v[136:137], off offset:256
	global_load_dwordx4 v[148:151], v[138:139], off
	global_load_dwordx4 v[144:147], v[138:139], off offset:256
	global_load_dwordx4 v[140:143], v[230:231], off
	s_nop 0
	global_load_dwordx4 v[136:139], v[230:231], off offset:256
	global_load_dwordx4 v[132:135], v[232:233], off
	global_load_dwordx4 v[128:131], v[232:233], off offset:256
	s_and_b64 vcc, exec, s[0:1]
	s_mov_b64 s[0:1], -1
	s_waitcnt vmcnt(0)
	v_lshlrev_b32_e32 v230, 16, v198
	v_and_b32_e32 v231, 0xffff0000, v198
	v_lshlrev_b32_e32 v198, 16, v199
	v_and_b32_e32 v199, 0xffff0000, v199
	v_lshlrev_b32_e32 v238, 16, v204
	v_and_b32_e32 v239, 0xffff0000, v204
	v_lshlrev_b32_e32 v232, 16, v200
	v_and_b32_e32 v233, 0xffff0000, v200
	v_lshlrev_b32_e32 v200, 16, v201
	v_and_b32_e32 v201, 0xffff0000, v201
	v_lshlrev_b32_e32 v236, 16, v202
	v_and_b32_e32 v237, 0xffff0000, v202
	v_lshlrev_b32_e32 v202, 16, v203
	v_and_b32_e32 v203, 0xffff0000, v203
	v_lshlrev_b32_e32 v204, 16, v205
	v_and_b32_e32 v205, 0xffff0000, v205
	v_pk_add_f32 v[126:127], v[126:127], v[198:199]
	v_pk_add_f32 v[124:125], v[124:125], v[230:231]
	v_pk_add_f32 v[108:109], v[108:109], v[238:239]
	v_lshlrev_b32_e32 v198, 16, v206
	v_and_b32_e32 v199, 0xffff0000, v206
	v_pk_add_f32 v[122:123], v[122:123], v[200:201]
	v_pk_add_f32 v[120:121], v[120:121], v[232:233]
	v_pk_add_f32 v[118:119], v[118:119], v[202:203]
	v_pk_add_f32 v[116:117], v[116:117], v[236:237]
	v_pk_add_f32 v[110:111], v[110:111], v[204:205]
	global_store_dwordx4 v[234:235], v[124:127], off
	global_store_dwordx4 v[234:235], v[120:123], off offset:16
	global_store_dwordx4 v[234:235], v[116:119], off offset:512
	global_store_dwordx4 v[234:235], v[108:111], off offset:528
	v_lshlrev_b32_e32 v200, 16, v207
	v_and_b32_e32 v201, 0xffff0000, v207
	v_pk_add_f32 v[108:109], v[112:113], v[198:199]
	v_lshlrev_b64 v[112:113], 12, v[226:227]
	v_lshl_add_u64 v[112:113], s[68:69], 0, v[112:113]
	v_pk_add_f32 v[110:111], v[114:115], v[200:201]
	v_lshl_add_u64 v[112:113], v[112:113], 0, v[182:183]
	global_store_dwordx4 v[112:113], v[108:111], off
	v_lshlrev_b32_e32 v116, 16, v208
	v_and_b32_e32 v117, 0xffff0000, v208
	v_lshlrev_b32_e32 v108, 16, v212
	v_and_b32_e32 v109, 0xffff0000, v212
	v_lshlrev_b32_e32 v110, 16, v213
	v_and_b32_e32 v111, 0xffff0000, v213
	v_pk_add_f32 v[94:95], v[94:95], v[110:111]
	v_pk_add_f32 v[92:93], v[92:93], v[108:109]
	global_store_dwordx4 v[112:113], v[92:95], off offset:528
	v_lshlrev_b32_e32 v118, 16, v209
	v_and_b32_e32 v119, 0xffff0000, v209
	v_lshlrev_b32_e32 v92, 16, v214
	v_and_b32_e32 v93, 0xffff0000, v214
	v_pk_add_f32 v[92:93], v[96:97], v[92:93]
	v_lshlrev_b64 v[96:97], 12, v[228:229]
	v_lshlrev_b32_e32 v94, 16, v215
	v_and_b32_e32 v95, 0xffff0000, v215
	v_lshl_add_u64 v[96:97], s[68:69], 0, v[96:97]
	v_pk_add_f32 v[94:95], v[98:99], v[94:95]
	v_lshl_add_u64 v[96:97], v[96:97], 0, v[182:183]
	global_store_dwordx4 v[96:97], v[92:95], off
	v_pk_add_f32 v[106:107], v[106:107], v[118:119]
	v_pk_add_f32 v[104:105], v[104:105], v[116:117]
	v_lshlrev_b32_e32 v92, 16, v220
	v_and_b32_e32 v93, 0xffff0000, v220
	v_lshlrev_b32_e32 v94, 16, v221
	v_and_b32_e32 v95, 0xffff0000, v221
	v_pk_add_f32 v[78:79], v[78:79], v[94:95]
	v_pk_add_f32 v[76:77], v[76:77], v[92:93]
	global_store_dwordx4 v[96:97], v[76:79], off offset:528
	global_store_dwordx4 v[112:113], v[104:107], off offset:16
	s_nop 0
	v_lshlrev_b32_e32 v76, 16, v222
	v_and_b32_e32 v77, 0xffff0000, v222
	v_pk_add_f32 v[76:77], v[80:81], v[76:77]
	v_lshlrev_b64 v[80:81], 12, v[190:191]
	v_lshlrev_b32_e32 v78, 16, v223
	v_and_b32_e32 v79, 0xffff0000, v223
	v_lshl_add_u64 v[80:81], s[68:69], 0, v[80:81]
	v_pk_add_f32 v[78:79], v[82:83], v[78:79]
	v_lshl_add_u64 v[80:81], v[80:81], 0, v[182:183]
	v_lshlrev_b32_e32 v104, 16, v210
	v_and_b32_e32 v105, 0xffff0000, v210
	v_lshlrev_b32_e32 v106, 16, v211
	v_and_b32_e32 v107, 0xffff0000, v211
	global_store_dwordx4 v[80:81], v[76:79], off
	v_pk_add_f32 v[102:103], v[102:103], v[106:107]
	v_pk_add_f32 v[100:101], v[100:101], v[104:105]
	v_lshlrev_b32_e32 v76, 16, v162
	v_and_b32_e32 v77, 0xffff0000, v162
	v_lshlrev_b32_e32 v78, 16, v163
	v_and_b32_e32 v79, 0xffff0000, v163
	v_pk_add_f32 v[66:67], v[66:67], v[78:79]
	v_pk_add_f32 v[64:65], v[64:65], v[76:77]
	global_store_dwordx4 v[112:113], v[100:103], off offset:512
	global_store_dwordx4 v[80:81], v[64:67], off offset:528
	s_nop 0
	v_lshlrev_b32_e32 v100, 16, v216
	v_and_b32_e32 v101, 0xffff0000, v216
	v_lshlrev_b32_e32 v102, 16, v217
	v_and_b32_e32 v103, 0xffff0000, v217
	v_lshlrev_b32_e32 v64, 16, v156
	v_and_b32_e32 v65, 0xffff0000, v156
	v_pk_add_f32 v[90:91], v[90:91], v[102:103]
	v_pk_add_f32 v[88:89], v[88:89], v[100:101]
	v_pk_add_f32 v[60:61], v[60:61], v[64:65]
	v_lshlrev_b64 v[64:65], 12, v[188:189]
	global_store_dwordx4 v[96:97], v[88:91], off offset:16
	v_lshlrev_b32_e32 v66, 16, v157
	v_and_b32_e32 v67, 0xffff0000, v157
	v_lshlrev_b32_e32 v88, 16, v218
	v_and_b32_e32 v89, 0xffff0000, v218
	v_lshlrev_b32_e32 v90, 16, v219
	v_and_b32_e32 v91, 0xffff0000, v219
	v_lshl_add_u64 v[64:65], s[68:69], 0, v[64:65]
	v_pk_add_f32 v[86:87], v[86:87], v[90:91]
	v_pk_add_f32 v[84:85], v[84:85], v[88:89]
	v_pk_add_f32 v[62:63], v[62:63], v[66:67]
	v_lshl_add_u64 v[64:65], v[64:65], 0, v[182:183]
	global_store_dwordx4 v[96:97], v[84:87], off offset:512
	global_store_dwordx4 v[64:65], v[60:63], off
	s_nop 0
	v_lshlrev_b32_e32 v84, 16, v224
	v_and_b32_e32 v85, 0xffff0000, v224
	v_lshlrev_b32_e32 v86, 16, v225
	v_and_b32_e32 v87, 0xffff0000, v225
	v_lshlrev_b32_e32 v60, 16, v154
	v_and_b32_e32 v61, 0xffff0000, v154
	v_lshlrev_b32_e32 v62, 16, v155
	v_and_b32_e32 v63, 0xffff0000, v155
	v_pk_add_f32 v[74:75], v[74:75], v[86:87]
	v_pk_add_f32 v[72:73], v[72:73], v[84:85]
	v_pk_add_f32 v[46:47], v[46:47], v[62:63]
	v_pk_add_f32 v[44:45], v[44:45], v[60:61]
	global_store_dwordx4 v[80:81], v[72:75], off offset:16
	global_store_dwordx4 v[64:65], v[44:47], off offset:528
	s_nop 0
	v_lshlrev_b32_e32 v72, 16, v160
	v_and_b32_e32 v73, 0xffff0000, v160
	v_lshlrev_b32_e32 v74, 16, v161
	v_and_b32_e32 v75, 0xffff0000, v161
	v_lshlrev_b32_e32 v44, 16, v148
	v_and_b32_e32 v45, 0xffff0000, v148
	v_pk_add_f32 v[70:71], v[70:71], v[74:75]
	v_pk_add_f32 v[68:69], v[68:69], v[72:73]
	v_pk_add_f32 v[44:45], v[48:49], v[44:45]
	v_lshlrev_b64 v[48:49], 12, v[186:187]
	global_store_dwordx4 v[80:81], v[68:71], off offset:512
	v_lshlrev_b32_e32 v46, 16, v149
	v_and_b32_e32 v47, 0xffff0000, v149
	v_lshlrev_b32_e32 v68, 16, v158
	v_and_b32_e32 v69, 0xffff0000, v158
	v_lshlrev_b32_e32 v70, 16, v159
	v_and_b32_e32 v71, 0xffff0000, v159
	v_lshl_add_u64 v[48:49], s[68:69], 0, v[48:49]
	v_pk_add_f32 v[58:59], v[58:59], v[70:71]
	v_pk_add_f32 v[56:57], v[56:57], v[68:69]
	v_pk_add_f32 v[46:47], v[50:51], v[46:47]
	v_lshl_add_u64 v[48:49], v[48:49], 0, v[182:183]
	global_store_dwordx4 v[64:65], v[56:59], off offset:16
	global_store_dwordx4 v[48:49], v[44:47], off
	s_nop 0
	v_lshlrev_b32_e32 v56, 16, v152
	v_and_b32_e32 v57, 0xffff0000, v152
	v_lshlrev_b32_e32 v58, 16, v153
	v_and_b32_e32 v59, 0xffff0000, v153
	v_lshlrev_b32_e32 v44, 16, v146
	v_and_b32_e32 v45, 0xffff0000, v146
	v_lshlrev_b32_e32 v46, 16, v147
	v_and_b32_e32 v47, 0xffff0000, v147
	v_pk_add_f32 v[54:55], v[54:55], v[58:59]
	v_pk_add_f32 v[52:53], v[52:53], v[56:57]
	v_pk_add_f32 v[30:31], v[30:31], v[46:47]
	v_pk_add_f32 v[28:29], v[28:29], v[44:45]
	global_store_dwordx4 v[64:65], v[52:55], off offset:512
	global_store_dwordx4 v[48:49], v[28:31], off offset:528
	s_nop 0
	v_lshlrev_b32_e32 v52, 16, v150
	v_and_b32_e32 v53, 0xffff0000, v150
	v_lshlrev_b32_e32 v54, 16, v151
	v_and_b32_e32 v55, 0xffff0000, v151
	v_lshlrev_b32_e32 v28, 16, v140
	v_and_b32_e32 v29, 0xffff0000, v140
	v_pk_add_f32 v[42:43], v[42:43], v[54:55]
	v_pk_add_f32 v[40:41], v[40:41], v[52:53]
	v_pk_add_f32 v[28:29], v[32:33], v[28:29]
	v_lshlrev_b64 v[32:33], 12, v[184:185]
	global_store_dwordx4 v[48:49], v[40:43], off offset:16
	v_lshlrev_b32_e32 v30, 16, v141
	v_and_b32_e32 v31, 0xffff0000, v141
	v_lshlrev_b32_e32 v40, 16, v144
	v_and_b32_e32 v41, 0xffff0000, v144
	v_lshlrev_b32_e32 v42, 16, v145
	v_and_b32_e32 v43, 0xffff0000, v145
	v_lshl_add_u64 v[32:33], s[68:69], 0, v[32:33]
	v_pk_add_f32 v[38:39], v[38:39], v[42:43]
	v_pk_add_f32 v[36:37], v[36:37], v[40:41]
	v_pk_add_f32 v[30:31], v[34:35], v[30:31]
	v_lshl_add_u64 v[32:33], v[32:33], 0, v[182:183]
	global_store_dwordx4 v[48:49], v[36:39], off offset:512
	global_store_dwordx4 v[32:33], v[28:31], off
	s_nop 0
	v_lshlrev_b32_e32 v36, 16, v142
	v_and_b32_e32 v37, 0xffff0000, v142
	v_lshlrev_b32_e32 v38, 16, v143
	v_and_b32_e32 v39, 0xffff0000, v143
	v_lshlrev_b32_e32 v28, 16, v138
	v_and_b32_e32 v29, 0xffff0000, v138
	v_lshlrev_b32_e32 v30, 16, v139
	v_and_b32_e32 v31, 0xffff0000, v139
	v_pk_add_f32 v[26:27], v[26:27], v[38:39]
	v_pk_add_f32 v[24:25], v[24:25], v[36:37]
	v_pk_add_f32 v[14:15], v[14:15], v[30:31]
	v_pk_add_f32 v[12:13], v[12:13], v[28:29]
	global_store_dwordx4 v[32:33], v[24:27], off offset:16
	global_store_dwordx4 v[32:33], v[12:15], off offset:528
	s_nop 0
	v_lshlrev_b32_e32 v24, 16, v136
	v_and_b32_e32 v25, 0xffff0000, v136
	v_lshlrev_b32_e32 v26, 16, v137
	v_and_b32_e32 v27, 0xffff0000, v137
	v_lshlrev_b32_e32 v12, 16, v132
	v_and_b32_e32 v13, 0xffff0000, v132
	v_pk_add_f32 v[22:23], v[22:23], v[26:27]
	v_pk_add_f32 v[20:21], v[20:21], v[24:25]
	v_pk_add_f32 v[12:13], v[16:17], v[12:13]
	v_lshlrev_b64 v[16:17], 12, v[180:181]
	global_store_dwordx4 v[32:33], v[20:23], off offset:512
	v_lshlrev_b32_e32 v14, 16, v133
	v_and_b32_e32 v15, 0xffff0000, v133
	v_lshlrev_b32_e32 v20, 16, v134
	v_and_b32_e32 v21, 0xffff0000, v134
	v_lshlrev_b32_e32 v22, 16, v135
	v_and_b32_e32 v23, 0xffff0000, v135
	v_lshl_add_u64 v[16:17], s[68:69], 0, v[16:17]
	v_pk_add_f32 v[14:15], v[18:19], v[14:15]
	v_lshl_add_u64 v[16:17], v[16:17], 0, v[182:183]
	v_pk_add_f32 v[10:11], v[10:11], v[22:23]
	v_pk_add_f32 v[8:9], v[8:9], v[20:21]
	global_store_dwordx4 v[16:17], v[12:15], off
	global_store_dwordx4 v[16:17], v[8:11], off offset:16
	s_nop 0
	v_lshlrev_b32_e32 v12, 16, v130
	v_lshlrev_b32_e32 v8, 16, v128
	v_and_b32_e32 v9, 0xffff0000, v128
	v_lshlrev_b32_e32 v10, 16, v129
	v_and_b32_e32 v11, 0xffff0000, v129
	v_and_b32_e32 v13, 0xffff0000, v130
	v_lshlrev_b32_e32 v14, 16, v131
	v_and_b32_e32 v15, 0xffff0000, v131
	v_pk_add_f32 v[6:7], v[6:7], v[10:11]
	v_pk_add_f32 v[4:5], v[4:5], v[8:9]
	v_pk_add_f32 v[2:3], v[2:3], v[14:15]
	v_pk_add_f32 v[0:1], v[0:1], v[12:13]
	global_store_dwordx4 v[16:17], v[4:7], off offset:512
	global_store_dwordx4 v[16:17], v[0:3], off offset:528
	s_cbranch_vccnz .LBB0_675
	s_andn2_b64 vcc, exec, s[6:7]
	s_cbranch_vccnz .LBB0_674
	s_barrier
	s_branch .LBB0_674
